# v20 + phase-1 norm loop: next-row prefetch issued after the per-row parameter loads, counted waits (vmcnt 8 / 6) keep it in flight across the row
# baseline (speedup 1.0000x reference)
; template <int PH>
; __device__ __forceinline__ void run_phase(const Args& args, LAS unsigned char* lds) {
;     ...
;         if (EN(1) && (ph == 1 || ph == 6 || ph == 9 || ph == 15)) {
;             const int layer = ph >= 9 ? 1 : 0; const bool ffn = (ph == 6 || ph == 15);
;             const float* g = (ffn ? args.in[7] : args.in[6]) + layer * D;
;             const float* srcL = ph == 1 ? x_in : XR; const float* srcC = ph == 1 ? ctx_in : XR + (size_t)ML * D;
;             const float* modL = MOD + layer * 9 * MODW + (ffn ? 3 : 0) * D;
;             const int rend = ph == 15 ? ML : MT;
;             f32x4 v[8], nv[8];
;             if (gw < rend) { const float* xr = gw < ML ? srcL + (size_t)gw * D : srcC + (size_t)(gw - ML) * D;
; #pragma unroll
;                 for (int j = 0; j < 8; ++j) v[j] = ((const f32x4*)xr)[lane + 64 * j]; }
;             for (int row = gw; row < rend; row += NGW) {
;                 const int nrow = row + NGW;
;                 if (nrow < rend) { const float* xn = nrow < ML ? srcL + (size_t)nrow * D : srcC + (size_t)(nrow - ML) * D;
; #pragma unroll
;                     for (int j = 0; j < 8; ++j) nv[j] = ((const f32x4*)xn)[lane + 64 * j]; }
;                 const float* mr = modL + (row < ML ? (row >> 11) : 8) * MODW;
.LBB0_148:
	s_cmp_lt_i32 s86, 2
	s_cselect_b64 s[0:1], -1, 0
	s_cmp_gt_i32 s87, 1
	s_cselect_b64 s[2:3], -1, 0
	s_and_b64 s[0:1], s[0:1], s[2:3]
	s_andn2_b64 vcc, exec, s[0:1]
	s_cbranch_vccnz .LBB0_219
	v_readfirstlane_b32 s0, v184
	s_lshr_b32 s0, s0, 6
	s_lshl_b32 s1, s33, 3
	s_add_i32 s22, s0, s1
	s_lshl_b32 s2, s88, 3
	s_add_u32 s23, s84, 0x100000
	v_and_b32_e32 v66, 63, v184
	s_addc_u32 s24, s85, 0
	s_cmpk_gt_i32 s22, 0x47ff
	v_lshlrev_b32_e32 v64, 3, v66
	s_cbranch_scc1 .LBB0_154
	s_add_i32 s3, s22, 0xffffc000
	s_ashr_i32 s4, s22, 31
	s_cmpk_lt_i32 s22, 0x4000
	s_cselect_b32 s5, s4, 0
	s_cselect_b32 s4, s22, s3
	s_cselect_b32 s3, s65, s69
	s_cselect_b32 s6, s64, s68
	s_lshl_b64 s[4:5], s[4:5], 13
	s_add_u32 s4, s6, s4
	s_addc_u32 s5, s3, s5
	v_mov_b32_e32 v9, 0
	v_lshlrev_b32_e32 v8, 4, v66
	v_lshl_add_u64 v[0:1], s[4:5], 0, v[8:9]
	s_movk_i32 s3, 0x1000
	v_add_co_u32_e32 v0, vcc, s3, v0
	global_load_dwordx4 v[60:63], v8, s[4:5]
	global_load_dwordx4 v[56:59], v8, s[4:5] offset:1024
	global_load_dwordx4 v[52:55], v8, s[4:5] offset:2048
	global_load_dwordx4 v[48:51], v8, s[4:5] offset:3072
	v_addc_co_u32_e32 v1, vcc, 0, v1, vcc
	global_load_dwordx4 v[44:47], v[0:1], off
	global_load_dwordx4 v[40:43], v[0:1], off offset:1024
	global_load_dwordx4 v[4:7], v[0:1], off offset:2048
	s_nop 0
	global_load_dwordx4 v[0:3], v[0:1], off offset:3072
	v_mbcnt_lo_u32_b32 v10, -1, 0
	v_mbcnt_hi_u32_b32 v10, -1, v10
	v_and_b32_e32 v11, 64, v10
	v_add_u32_e32 v11, 64, v11
	v_xor_b32_e32 v12, 1, v10
	v_cmp_lt_i32_e32 vcc, v12, v11
	s_add_i32 s10, s22, s2
	s_ashr_i32 s11, s10, 31
	v_cndmask_b32_e32 v12, v10, v12, vcc
	v_lshlrev_b32_e32 v67, 2, v12
	v_xor_b32_e32 v12, 2, v10
	v_cmp_lt_i32_e32 vcc, v12, v11
	s_ashr_i32 s3, s2, 31
	s_ashr_i32 s4, s1, 31
	v_cndmask_b32_e32 v12, v10, v12, vcc
	v_lshlrev_b32_e32 v81, 2, v12
	v_xor_b32_e32 v12, 4, v10
	v_cmp_lt_i32_e32 vcc, v12, v11
	v_or_b32_e32 v16, 0x100, v66
	s_add_u32 s0, s0, s1
	v_cndmask_b32_e32 v12, v10, v12, vcc
	v_lshlrev_b32_e32 v82, 2, v12
	v_xor_b32_e32 v12, 8, v10
	v_cmp_lt_i32_e32 vcc, v12, v11
	v_or_b32_e32 v18, 0x140, v66
	v_lshl_add_u64 v[68:69], s[76:77], 0, v[8:9]
	v_cndmask_b32_e32 v12, v10, v12, vcc
	v_lshlrev_b32_e32 v83, 2, v12
	v_xor_b32_e32 v12, 16, v10
	v_cmp_lt_i32_e32 vcc, v12, v11
	v_lshlrev_b32_e32 v8, 4, v16
	s_addc_u32 s1, 0, s4
	v_cndmask_b32_e32 v12, v10, v12, vcc
	v_lshlrev_b32_e32 v84, 2, v12
	v_xor_b32_e32 v12, 32, v10
	v_or_b32_e32 v20, 0x180, v66
	v_lshl_add_u64 v[70:71], s[76:77], 0, v[8:9]
	v_lshlrev_b32_e32 v8, 4, v18
	s_lshl_b64 s[0:1], s[0:1], 12
	v_cmp_lt_i32_e32 vcc, v12, v11
	v_or_b32_e32 v22, 0x1c0, v66
	v_lshl_add_u64 v[72:73], s[76:77], 0, v[8:9]
	v_lshlrev_b32_e32 v8, 4, v20
	s_add_u32 s0, s84, s0
	v_cndmask_b32_e32 v10, v10, v12, vcc
	v_lshl_add_u64 v[74:75], s[76:77], 0, v[8:9]
	v_lshlrev_b32_e32 v8, 4, v22
	v_mov_b32_e32 v65, v9
	s_addc_u32 s1, s85, s1
	v_lshlrev_b32_e32 v85, 2, v10
	v_or_b32_e32 v10, 64, v66
	v_or_b32_e32 v12, 0x80, v66
	v_or_b32_e32 v14, 0xc0, v66
	v_lshl_add_u64 v[76:77], s[76:77], 0, v[8:9]
	v_lshl_add_u64 v[8:9], s[0:1], 0, v[64:65]
	s_mov_b64 s[0:1], 0x14800800
	v_lshl_add_u64 v[78:79], v[8:9], 0, s[0:1]
	s_lshl_b64 s[4:5], s[2:3], 12
	v_mov_b32_e32 v65, 0x358637bd
	s_mov_b32 s14, 0xf800000
	v_mov_b32_e32 v86, 0x260
	s_movk_i32 s15, 0x7fff
	v_lshlrev_b32_e32 v87, 4, v10
	v_lshlrev_b32_e32 v88, 4, v12
	v_lshlrev_b32_e32 v89, 4, v14
	v_lshlrev_b32_e32 v90, 4, v16
	v_lshlrev_b32_e32 v91, 4, v18
	v_lshlrev_b32_e32 v92, 4, v20
	v_lshlrev_b32_e32 v93, 4, v22
	v_mov_b32_e32 v94, 1
	s_mov_b32 s0, s22
	s_waitcnt vmcnt(0)
	s_branch .LBB0_152
; template <int PH>
; __device__ __forceinline__ void run_phase(const Args& args, LAS unsigned char* lds) {
;     ...
;             for (int row = gw; row < rend; row += NGW) {
;                 const int nrow = row + NGW;
;                 if (nrow < rend) { const float* xn = nrow < ML ? srcL + (size_t)nrow * D : srcC + (size_t)(nrow - ML) * D;
; #pragma unroll
;                     for (int j = 0; j < 8; ++j) nv[j] = ((const f32x4*)xn)[lane + 64 * j]; }
;                 const float* mr = modL + (row < ML ? (row >> 11) : 8) * MODW;
;                 float ss = 0.f;
; #pragma unroll
;                 for (int j = 0; j < 8; ++j) ss += (v[j].x * v[j].x + v[j].y * v[j].y) + (v[j].z * v[j].z + v[j].w * v[j].w);
;                 const float rs = 1.0f / sqrtf(wave_sum(ss) * (1.0f / D) + NEPS);
;                 u32x2* op = (u32x2*)(Hb + (size_t)row * D);
; #pragma unroll
;                 for (int j = 0; j < 8; ++j) { const int c4 = lane + 64 * j; const f32x4 gg = ((const f32x4*)g)[c4], sh = ((const f32x4*)mr)[c4], sc = ((const f32x4*)(mr + D))[c4];
.LBB0_151:
	v_mov_b32_e32 v98, v61
	v_mov_b32_e32 v99, v57
	v_mov_b32_e32 v96, v60
	v_mov_b32_e32 v97, v56
	v_pk_mul_f32 v[98:99], v[98:99], v[98:99]
	v_mov_b32_e32 v100, v63
	v_mov_b32_e32 v101, v59
	v_pk_fma_f32 v[96:97], v[96:97], v[96:97], v[98:99]
	v_mov_b32_e32 v98, v62
	v_mov_b32_e32 v99, v58
	v_pk_mul_f32 v[100:101], v[100:101], v[100:101]
	v_mul_f32_e32 v80, v44, v44
	v_pk_fma_f32 v[98:99], v[98:99], v[98:99], v[100:101]
	v_pk_mul_f32 v[100:101], v[52:53], v[52:53]
	v_pk_add_f32 v[96:97], v[96:97], v[98:99]
	v_pk_mul_f32 v[98:99], v[54:55], v[54:55]
	v_pk_add_f32 v[96:97], v[96:97], v[96:97] op_sel:[0,1] op_sel_hi:[1,0]
	v_pk_mov_b32 v[102:103], v[100:101], v[98:99] op_sel:[1,0]
	v_mov_b32_e32 v101, v99
	v_pk_add_f32 v[98:99], v[102:103], v[100:101]
	v_mul_f32_e32 v100, v45, v45
	v_pk_add_f32 v[98:99], v[98:99], v[98:99] op_sel:[0,1] op_sel_hi:[1,0]
	v_mov_b32_e32 v97, v80
	v_mov_b32_e32 v99, v100
	v_mul_f32_e32 v80, v49, v49
	v_mul_f32_e32 v101, v46, v46
	v_pk_add_f32 v[96:97], v[96:97], v[98:99]
	v_pk_fma_f32 v[98:99], v[48:49], v[48:49], v[80:81] op_sel_hi:[1,1,0]
	v_mul_f32_e32 v80, v51, v51
	v_mul_f32_e32 v102, v47, v47
	v_mov_b32_e32 v99, v101
	v_pk_fma_f32 v[100:101], v[50:51], v[50:51], v[80:81] op_sel_hi:[1,1,0]
	s_add_i32 s25, s0, s2
	v_mov_b32_e32 v101, v102
	v_pk_add_f32 v[98:99], v[98:99], v[100:101]
	v_pk_mul_f32 v[100:101], v[40:41], v[40:41]
	v_pk_add_f32 v[96:97], v[96:97], v[98:99]
	v_pk_mul_f32 v[98:99], v[42:43], v[42:43]
	s_min_i32 s0, s0, 0x4000
	v_pk_mov_b32 v[102:103], v[100:101], v[98:99] op_sel:[1,0]
	v_mov_b32_e32 v101, v99
	v_pk_add_f32 v[98:99], v[102:103], v[100:101]
	s_lshr_b32 s0, s0, 11
	v_mul_f32_e32 v80, v0, v0
	v_mul_f32_e32 v100, v1, v1
	v_pk_add_f32 v[96:97], v[96:97], v[96:97] op_sel:[0,1] op_sel_hi:[1,0]
	v_pk_add_f32 v[98:99], v[98:99], v[98:99] op_sel:[0,1] op_sel_hi:[1,0]
	s_mulk_i32 s0, 0x3000
	v_mov_b32_e32 v97, v80
	v_mov_b32_e32 v99, v100
	v_mul_f32_e32 v80, v5, v5
	s_ashr_i32 s1, s0, 31
	v_mul_f32_e32 v101, v2, v2
	v_pk_add_f32 v[96:97], v[96:97], v[98:99]
	v_pk_fma_f32 v[98:99], v[4:5], v[4:5], v[80:81] op_sel_hi:[1,1,0]
	v_mul_f32_e32 v80, v7, v7
	v_mul_f32_e32 v102, v3, v3
	v_mov_b32_e32 v99, v101
	v_pk_fma_f32 v[100:101], v[6:7], v[6:7], v[80:81] op_sel_hi:[1,1,0]
	s_lshl_b64 s[0:1], s[0:1], 2
	v_mov_b32_e32 v101, v102
	s_add_u32 s6, s23, s0
	v_pk_add_f32 v[98:99], v[98:99], v[100:101]
	s_addc_u32 s7, s24, s1
	v_pk_add_f32 v[96:97], v[96:97], v[98:99]
	s_add_u32 s8, s6, 0x2000
	v_add_f32_e32 v80, v96, v97
	global_load_dwordx4 v[96:99], v[68:69], off
	s_addc_u32 s9, s7, 0
	global_load_dwordx4 v[100:103], v95, s[8:9]
	global_load_dwordx4 v[104:107], v95, s[6:7]
	global_load_dwordx4 v[120:123], v[68:69], off offset:1024
	global_load_dwordx4 v[124:127], v87, s[8:9]
	global_load_dwordx4 v[128:131], v95, s[6:7] offset:1024
	global_load_dwordx4 v[132:135], v[68:69], off offset:2048
	global_load_dwordx4 v[136:139], v88, s[8:9]
	global_load_dwordx4 v[140:143], v95, s[6:7] offset:2048
	global_load_dwordx4 v[144:147], v[68:69], off offset:3072
	global_load_dwordx4 v[148:151], v89, s[8:9]
	global_load_dwordx4 v[152:155], v95, s[6:7] offset:3072
	global_load_dwordx4 v[156:159], v[70:71], off
	global_load_dwordx4 v[160:163], v90, s[8:9]
	global_load_dwordx4 v[164:167], v90, s[6:7]
	global_load_dwordx4 v[168:171], v[72:73], off
	global_load_dwordx4 v[172:175], v91, s[8:9]
	global_load_dwordx4 v[176:179], v91, s[6:7]
	global_load_dwordx4 v[180:183], v[74:75], off
	global_load_dwordx4 v[188:191], v92, s[8:9]
	global_load_dwordx4 v[192:195], v92, s[6:7]
	global_load_dwordx4 v[196:199], v[76:77], off
	global_load_dwordx4 v[200:203], v93, s[8:9]
	global_load_dwordx4 v[204:207], v93, s[6:7]
	s_cmpk_gt_i32 s10, 0x47ff
	s_cbranch_scc1 .Lp1_last
	s_add_i32 s1, s10, 0xffffc000
	s_cmpk_lt_i32 s10, 0x4000
	s_cselect_b32 s7, s11, 0
	s_cselect_b32 s6, s10, s1
	s_cselect_b32 s1, s65, s69
	s_cselect_b32 s8, s64, s68
	s_lshl_b64 s[6:7], s[6:7], 13
	s_add_u32 s6, s8, s6
	s_addc_u32 s7, s1, s7
	global_load_dwordx4 v[36:39], v95, s[6:7]
	global_load_dwordx4 v[32:35], v95, s[6:7] offset:1024
	global_load_dwordx4 v[28:31], v95, s[6:7] offset:2048
	global_load_dwordx4 v[24:27], v95, s[6:7] offset:3072
	global_load_dwordx4 v[20:23], v90, s[6:7]
	global_load_dwordx4 v[16:19], v91, s[6:7]
	global_load_dwordx4 v[12:15], v92, s[6:7]
	global_load_dwordx4 v[8:11], v93, s[6:7]
	s_branch .Lp1_join

; __device__ __forceinline__ unsigned pk2(float lo, float hi) { return f2bf(lo) | (f2bf(hi) << 16); }
; template <int PH>
; __device__ __forceinline__ void run_phase(const Args& args, LAS unsigned char* lds) {
;     ...
;                 if (nrow < rend) { const float* xn = nrow < ML ? srcL + (size_t)nrow * D : srcC + (size_t)(nrow - ML) * D;
; #pragma unroll
;                     for (int j = 0; j < 8; ++j) nv[j] = ((const f32x4*)xn)[lane + 64 * j]; }
;                 const float* mr = modL + (row < ML ? (row >> 11) : 8) * MODW;
;                 float ss = 0.f;
; #pragma unroll
;                 for (int j = 0; j < 8; ++j) ss += (v[j].x * v[j].x + v[j].y * v[j].y) + (v[j].z * v[j].z + v[j].w * v[j].w);
;                 const float rs = 1.0f / sqrtf(wave_sum(ss) * (1.0f / D) + NEPS);
;                 u32x2* op = (u32x2*)(Hb + (size_t)row * D);
; #pragma unroll
;                 for (int j = 0; j < 8; ++j) { const int c4 = lane + 64 * j; const f32x4 gg = ((const f32x4*)g)[c4], sh = ((const f32x4*)mr)[c4], sc = ((const f32x4*)(mr + D))[c4];
;                     u32x2 w; w.x = pk2(v[j].x * rs * gg.x * (1.f + sc.x) + sh.x, v[j].y * rs * gg.y * (1.f + sc.y) + sh.y);
;                     w.y = pk2(v[j].z * rs * gg.z * (1.f + sc.z) + sh.z, v[j].w * rs * gg.w * (1.f + sc.w) + sh.w); op[c4] = w; }
.Lp1_join:
	ds_bpermute_b32 v108, v67, v80
	s_add_u32 s10, s10, s2
	s_addc_u32 s11, s11, s3
	s_cmpk_gt_i32 s25, 0x47ff
	s_waitcnt lgkmcnt(0)
	v_add_f32_e32 v80, v80, v108
	s_nop 1
	v_add_f32_dpp v80, v80, v80 quad_perm:[2,3,0,1] row_mask:0xf bank_mask:0xf
	s_nop 1
	v_add_f32_dpp v80, v80, v80 row_half_mirror row_mask:0xf bank_mask:0xf
	s_nop 1
	v_add_f32_dpp v80, v80, v80 row_mirror row_mask:0xf bank_mask:0xf
	ds_bpermute_b32 v108, v84, v80
	s_waitcnt lgkmcnt(0)
	v_add_f32_e32 v80, v80, v108
	ds_bpermute_b32 v108, v85, v80
	s_waitcnt lgkmcnt(0)
	v_add_f32_e32 v80, v80, v108
	v_fmamk_f32 v80, v80, 0x3a000000, v65
	v_mul_f32_e32 v108, 0x4f800000, v80
	v_cmp_gt_f32_e32 vcc, s14, v80
	s_waitcnt vmcnt(8)
	v_mov_b32_e32 v113, v106
	v_cndmask_b32_e32 v80, v80, v108, vcc
	v_sqrt_f32_e32 v108, v80
	v_mov_b32_e32 v106, v105
	v_mov_b32_e32 v105, v58
	v_mov_b32_e32 v58, v57
	v_add_u32_e32 v109, -1, v108
	v_fma_f32 v110, -v109, v108, v80
	v_cmp_ge_f32_e64 s[0:1], 0, v110
	v_add_u32_e32 v110, 1, v108
	s_nop 0
	v_cndmask_b32_e64 v109, v108, v109, s[0:1]
	v_fma_f32 v108, -v110, v108, v80
	v_cmp_lt_f32_e64 s[0:1], 0, v108
	s_nop 1
	v_cndmask_b32_e64 v108, v109, v110, s[0:1]
	v_mul_f32_e32 v109, 0x37800000, v108
	v_cndmask_b32_e32 v108, v108, v109, vcc
	v_cmp_class_f32_e32 vcc, v80, v86
	s_nop 1
	v_cndmask_b32_e32 v80, v108, v80, vcc
	v_div_scale_f32 v108, s[0:1], v80, v80, 1.0
	v_rcp_f32_e32 v109, v108
	s_mov_b32 s0, s25
	v_fma_f32 v110, -v108, v109, 1.0
	v_fmac_f32_e32 v109, v110, v109
	v_div_scale_f32 v110, vcc, 1.0, v80, 1.0
	v_mul_f32_e32 v111, v110, v109
	v_fma_f32 v112, -v108, v111, v110
	v_fmac_f32_e32 v111, v112, v109
	v_fma_f32 v108, -v108, v111, v110
	v_div_fmas_f32 v108, v108, v109, v111
	v_div_fixup_f32 v80, v108, v80, 1.0
	v_mov_b32_e32 v108, v60
	v_mov_b32_e32 v109, v62
	v_pk_mul_f32 v[108:109], v[108:109], v[80:81] op_sel_hi:[1,0]
	v_mov_b32_e32 v110, v96
	v_mov_b32_e32 v111, v98
	v_mov_b32_e32 v62, v61
	v_pk_mul_f32 v[108:109], v[110:111], v[108:109]
	v_mov_b32_e32 v111, v102
	v_pk_mul_f32 v[60:61], v[62:63], v[80:81] op_sel_hi:[1,0]
	v_mov_b32_e32 v98, v97
	v_mov_b32_e32 v102, v101
	v_mov_b32_e32 v110, v100
	v_pk_mul_f32 v[60:61], v[98:99], v[60:61]
	v_pk_add_f32 v[62:63], v[102:103], 1.0 op_sel_hi:[1,0]
	v_pk_add_f32 v[110:111], v[110:111], 1.0 op_sel_hi:[1,0]
	v_mov_b32_e32 v112, v104
	v_pk_fma_f32 v[60:61], v[62:63], v[60:61], v[106:107]
	v_pk_fma_f32 v[108:109], v[110:111], v[108:109], v[112:113]
	v_and_b32_sdwa v96, v61, v94 dst_sel:DWORD dst_unused:UNUSED_PAD src0_sel:WORD_1 src1_sel:DWORD
	v_and_b32_sdwa v97, v60, v94 dst_sel:DWORD dst_unused:UNUSED_PAD src0_sel:WORD_1 src1_sel:DWORD
	v_and_b32_sdwa v62, v109, v94 dst_sel:DWORD dst_unused:UNUSED_PAD src0_sel:WORD_1 src1_sel:DWORD
	v_and_b32_sdwa v63, v108, v94 dst_sel:DWORD dst_unused:UNUSED_PAD src0_sel:WORD_1 src1_sel:DWORD
	v_add3_u32 v61, v61, v96, s15
	v_add3_u32 v60, v60, v97, s15
	v_add3_u32 v63, v108, v63, s15
	v_add3_u32 v62, v109, v62, s15
	v_and_b32_e32 v61, 0xffff0000, v61
	v_and_b32_e32 v60, 0xffff0000, v60
	v_or_b32_sdwa v61, v61, v62 dst_sel:DWORD dst_unused:UNUSED_PAD src0_sel:DWORD src1_sel:WORD_1
	v_or_b32_sdwa v60, v60, v63 dst_sel:DWORD dst_unused:UNUSED_PAD src0_sel:DWORD src1_sel:WORD_1
	global_store_dwordx2 v[78:79], v[60:61], off offset:-2048
	s_nop 1
	v_mov_b64_e32 v[60:61], v[120:121]
	v_mov_b64_e32 v[62:63], v[122:123]
	s_nop 0
	s_nop 1
	v_mov_b64_e32 v[96:97], v[124:125]
	v_mov_b64_e32 v[98:99], v[126:127]
	s_nop 1
	v_mov_b64_e32 v[100:101], v[128:129]
	v_mov_b64_e32 v[102:103], v[130:131]
	v_mov_b32_e32 v104, v56
	v_pk_mul_f32 v[56:57], v[104:105], v[80:81] op_sel_hi:[1,0]
	v_pk_mul_f32 v[58:59], v[58:59], v[80:81] op_sel_hi:[1,0]
	v_mov_b32_e32 v105, v62
	v_mov_b32_e32 v107, v98
	v_mov_b32_e32 v62, v61
	v_mov_b32_e32 v98, v97
	v_mov_b32_e32 v104, v60
	v_mov_b32_e32 v106, v96
	v_mov_b32_e32 v109, v102
	v_mov_b32_e32 v102, v101
	v_pk_mul_f32 v[58:59], v[62:63], v[58:59]
	v_pk_add_f32 v[62:63], v[98:99], 1.0 op_sel_hi:[1,0]
	v_mov_b32_e32 v108, v100
	v_pk_mul_f32 v[56:57], v[104:105], v[56:57]
	v_pk_add_f32 v[60:61], v[106:107], 1.0 op_sel_hi:[1,0]
	v_pk_fma_f32 v[58:59], v[58:59], v[62:63], v[102:103]
	v_pk_fma_f32 v[56:57], v[56:57], v[60:61], v[108:109]
	v_and_b32_sdwa v62, v59, v94 dst_sel:DWORD dst_unused:UNUSED_PAD src0_sel:WORD_1 src1_sel:DWORD
	v_and_b32_sdwa v63, v58, v94 dst_sel:DWORD dst_unused:UNUSED_PAD src0_sel:WORD_1 src1_sel:DWORD
	v_and_b32_sdwa v60, v57, v94 dst_sel:DWORD dst_unused:UNUSED_PAD src0_sel:WORD_1 src1_sel:DWORD
	v_and_b32_sdwa v61, v56, v94 dst_sel:DWORD dst_unused:UNUSED_PAD src0_sel:WORD_1 src1_sel:DWORD
	v_add3_u32 v59, v59, v62, s15
	v_add3_u32 v58, v58, v63, s15
	v_add3_u32 v56, v56, v61, s15
	v_add3_u32 v57, v57, v60, s15
	v_and_b32_e32 v59, 0xffff0000, v59
	v_and_b32_e32 v58, 0xffff0000, v58
	v_or_b32_sdwa v57, v59, v57 dst_sel:DWORD dst_unused:UNUSED_PAD src0_sel:DWORD src1_sel:WORD_1
	v_or_b32_sdwa v56, v58, v56 dst_sel:DWORD dst_unused:UNUSED_PAD src0_sel:DWORD src1_sel:WORD_1
	global_store_dwordx2 v[78:79], v[56:57], off offset:-1536
	s_nop 1
	v_mov_b64_e32 v[56:57], v[132:133]
	v_mov_b64_e32 v[58:59], v[134:135]
	s_nop 0
	s_nop 1
	v_mov_b64_e32 v[60:61], v[136:137]
	v_mov_b64_e32 v[62:63], v[138:139]
	s_nop 1
	v_mov_b64_e32 v[96:97], v[140:141]
	v_mov_b64_e32 v[98:99], v[142:143]
	v_mov_b32_e32 v100, v52
	v_mov_b32_e32 v101, v54
	v_mov_b32_e32 v54, v53
	v_pk_mul_f32 v[52:53], v[100:101], v[80:81] op_sel_hi:[1,0]
	v_pk_mul_f32 v[54:55], v[54:55], v[80:81] op_sel_hi:[1,0]
	v_mov_b32_e32 v101, v58
	v_mov_b32_e32 v103, v62
	v_mov_b32_e32 v58, v57
	v_mov_b32_e32 v62, v61
	v_mov_b32_e32 v100, v56
	v_mov_b32_e32 v102, v60
; __device__ __forceinline__ unsigned pk2(float lo, float hi) { return f2bf(lo) | (f2bf(hi) << 16); }
; template <int PH>
; __device__ __forceinline__ void run_phase(const Args& args, LAS unsigned char* lds) {
;     ...
;                 u32x2* op = (u32x2*)(Hb + (size_t)row * D);
; #pragma unroll
;                 for (int j = 0; j < 8; ++j) { const int c4 = lane + 64 * j; const f32x4 gg = ((const f32x4*)g)[c4], sh = ((const f32x4*)mr)[c4], sc = ((const f32x4*)(mr + D))[c4];
;                     u32x2 w; w.x = pk2(v[j].x * rs * gg.x * (1.f + sc.x) + sh.x, v[j].y * rs * gg.y * (1.f + sc.y) + sh.y);
;                     w.y = pk2(v[j].z * rs * gg.z * (1.f + sc.z) + sh.z, v[j].w * rs * gg.w * (1.f + sc.w) + sh.w); op[c4] = w; }
	v_mov_b32_e32 v105, v98
	v_mov_b32_e32 v98, v97
	v_pk_mul_f32 v[54:55], v[54:55], v[58:59]
	v_pk_add_f32 v[58:59], v[62:63], 1.0 op_sel_hi:[1,0]
	v_mov_b32_e32 v104, v96
	v_pk_mul_f32 v[52:53], v[52:53], v[100:101]
	v_pk_add_f32 v[56:57], v[102:103], 1.0 op_sel_hi:[1,0]
	v_pk_fma_f32 v[54:55], v[54:55], v[58:59], v[98:99]
	v_pk_fma_f32 v[52:53], v[52:53], v[56:57], v[104:105]
	v_and_b32_sdwa v58, v55, v94 dst_sel:DWORD dst_unused:UNUSED_PAD src0_sel:WORD_1 src1_sel:DWORD
	v_and_b32_sdwa v59, v54, v94 dst_sel:DWORD dst_unused:UNUSED_PAD src0_sel:WORD_1 src1_sel:DWORD
	v_and_b32_sdwa v56, v53, v94 dst_sel:DWORD dst_unused:UNUSED_PAD src0_sel:WORD_1 src1_sel:DWORD
	v_and_b32_sdwa v57, v52, v94 dst_sel:DWORD dst_unused:UNUSED_PAD src0_sel:WORD_1 src1_sel:DWORD
	v_add3_u32 v55, v55, v58, s15
	v_add3_u32 v54, v54, v59, s15
	v_add3_u32 v52, v52, v57, s15
	v_add3_u32 v53, v53, v56, s15
	v_and_b32_e32 v55, 0xffff0000, v55
	v_and_b32_e32 v54, 0xffff0000, v54
	v_or_b32_sdwa v53, v55, v53 dst_sel:DWORD dst_unused:UNUSED_PAD src0_sel:DWORD src1_sel:WORD_1
	v_or_b32_sdwa v52, v54, v52 dst_sel:DWORD dst_unused:UNUSED_PAD src0_sel:DWORD src1_sel:WORD_1
	global_store_dwordx2 v[78:79], v[52:53], off offset:-1024
	s_nop 1
	v_mov_b64_e32 v[52:53], v[144:145]
	v_mov_b64_e32 v[54:55], v[146:147]
	s_nop 0
	s_nop 1
	v_mov_b64_e32 v[56:57], v[148:149]
	v_mov_b64_e32 v[58:59], v[150:151]
	s_nop 1
	v_mov_b64_e32 v[60:61], v[152:153]
	v_mov_b64_e32 v[62:63], v[154:155]
	v_mov_b32_e32 v96, v48
	v_mov_b32_e32 v97, v50
	v_mov_b32_e32 v50, v49
	v_pk_mul_f32 v[48:49], v[96:97], v[80:81] op_sel_hi:[1,0]
	v_pk_mul_f32 v[50:51], v[50:51], v[80:81] op_sel_hi:[1,0]
	v_mov_b32_e32 v97, v54
	v_mov_b32_e32 v99, v58
	v_mov_b32_e32 v54, v53
	v_mov_b32_e32 v58, v57
	v_mov_b32_e32 v96, v52
	v_mov_b32_e32 v98, v56
	v_mov_b32_e32 v101, v62
	v_mov_b32_e32 v62, v61
	v_pk_mul_f32 v[50:51], v[50:51], v[54:55]
	v_pk_add_f32 v[54:55], v[58:59], 1.0 op_sel_hi:[1,0]
	v_mov_b32_e32 v100, v60
	v_pk_mul_f32 v[48:49], v[48:49], v[96:97]
	v_pk_add_f32 v[52:53], v[98:99], 1.0 op_sel_hi:[1,0]
	v_pk_fma_f32 v[50:51], v[50:51], v[54:55], v[62:63]
	v_pk_fma_f32 v[48:49], v[48:49], v[52:53], v[100:101]
	v_and_b32_sdwa v54, v51, v94 dst_sel:DWORD dst_unused:UNUSED_PAD src0_sel:WORD_1 src1_sel:DWORD
	v_and_b32_sdwa v55, v50, v94 dst_sel:DWORD dst_unused:UNUSED_PAD src0_sel:WORD_1 src1_sel:DWORD
	v_and_b32_sdwa v52, v49, v94 dst_sel:DWORD dst_unused:UNUSED_PAD src0_sel:WORD_1 src1_sel:DWORD
	v_and_b32_sdwa v53, v48, v94 dst_sel:DWORD dst_unused:UNUSED_PAD src0_sel:WORD_1 src1_sel:DWORD
	v_add3_u32 v51, v51, v54, s15
	v_add3_u32 v50, v50, v55, s15
	v_add3_u32 v48, v48, v53, s15
	v_add3_u32 v49, v49, v52, s15
	v_and_b32_e32 v51, 0xffff0000, v51
	v_and_b32_e32 v50, 0xffff0000, v50
	v_or_b32_sdwa v49, v51, v49 dst_sel:DWORD dst_unused:UNUSED_PAD src0_sel:DWORD src1_sel:WORD_1
	v_or_b32_sdwa v48, v50, v48 dst_sel:DWORD dst_unused:UNUSED_PAD src0_sel:DWORD src1_sel:WORD_1
	global_store_dwordx2 v[78:79], v[48:49], off offset:-512
	s_nop 1
	v_mov_b64_e32 v[48:49], v[156:157]
	v_mov_b64_e32 v[50:51], v[158:159]
	s_nop 0
	s_nop 1
	v_mov_b64_e32 v[52:53], v[160:161]
	v_mov_b64_e32 v[54:55], v[162:163]
	s_nop 1
	v_mov_b64_e32 v[56:57], v[164:165]
	v_mov_b64_e32 v[58:59], v[166:167]
	v_mov_b32_e32 v60, v44
	v_mov_b32_e32 v61, v46
	v_mov_b32_e32 v46, v45
	v_pk_mul_f32 v[44:45], v[60:61], v[80:81] op_sel_hi:[1,0]
	v_pk_mul_f32 v[46:47], v[46:47], v[80:81] op_sel_hi:[1,0]
	v_mov_b32_e32 v61, v50
	v_mov_b32_e32 v63, v54
	v_mov_b32_e32 v50, v49
	v_mov_b32_e32 v54, v53
	v_mov_b32_e32 v60, v48
	v_mov_b32_e32 v62, v52
	v_mov_b32_e32 v97, v58
	v_mov_b32_e32 v58, v57
	v_pk_mul_f32 v[46:47], v[46:47], v[50:51]
	v_pk_add_f32 v[50:51], v[54:55], 1.0 op_sel_hi:[1,0]
	v_mov_b32_e32 v96, v56
	v_pk_mul_f32 v[44:45], v[44:45], v[60:61]
	v_pk_add_f32 v[48:49], v[62:63], 1.0 op_sel_hi:[1,0]
	v_pk_fma_f32 v[46:47], v[46:47], v[50:51], v[58:59]
	v_pk_fma_f32 v[44:45], v[44:45], v[48:49], v[96:97]
	v_and_b32_sdwa v50, v47, v94 dst_sel:DWORD dst_unused:UNUSED_PAD src0_sel:WORD_1 src1_sel:DWORD
	v_and_b32_sdwa v51, v46, v94 dst_sel:DWORD dst_unused:UNUSED_PAD src0_sel:WORD_1 src1_sel:DWORD
	v_and_b32_sdwa v48, v45, v94 dst_sel:DWORD dst_unused:UNUSED_PAD src0_sel:WORD_1 src1_sel:DWORD
	v_and_b32_sdwa v49, v44, v94 dst_sel:DWORD dst_unused:UNUSED_PAD src0_sel:WORD_1 src1_sel:DWORD
	v_add3_u32 v47, v47, v50, s15
	v_add3_u32 v46, v46, v51, s15
	v_add3_u32 v44, v44, v49, s15
	v_add3_u32 v45, v45, v48, s15
	v_and_b32_e32 v47, 0xffff0000, v47
	v_and_b32_e32 v46, 0xffff0000, v46
	v_or_b32_sdwa v45, v47, v45 dst_sel:DWORD dst_unused:UNUSED_PAD src0_sel:DWORD src1_sel:WORD_1
	v_or_b32_sdwa v44, v46, v44 dst_sel:DWORD dst_unused:UNUSED_PAD src0_sel:DWORD src1_sel:WORD_1
	global_store_dwordx2 v[78:79], v[44:45], off
	s_nop 1
	v_mov_b64_e32 v[44:45], v[168:169]
	v_mov_b64_e32 v[46:47], v[170:171]
	s_nop 0
	s_nop 1
	v_mov_b64_e32 v[48:49], v[172:173]
	v_mov_b64_e32 v[50:51], v[174:175]
	s_nop 1
	v_mov_b64_e32 v[52:53], v[176:177]
	v_mov_b64_e32 v[54:55], v[178:179]
	v_mov_b32_e32 v56, v40
	v_mov_b32_e32 v57, v42
	v_mov_b32_e32 v42, v41
	v_pk_mul_f32 v[40:41], v[56:57], v[80:81] op_sel_hi:[1,0]
	v_pk_mul_f32 v[42:43], v[42:43], v[80:81] op_sel_hi:[1,0]
	v_mov_b32_e32 v57, v46
	v_mov_b32_e32 v59, v50
	v_mov_b32_e32 v46, v45
	v_mov_b32_e32 v50, v49
	v_mov_b32_e32 v56, v44
	v_mov_b32_e32 v58, v48
	v_mov_b32_e32 v61, v54
	v_mov_b32_e32 v54, v53
	v_pk_mul_f32 v[42:43], v[42:43], v[46:47]
	v_pk_add_f32 v[46:47], v[50:51], 1.0 op_sel_hi:[1,0]
	v_mov_b32_e32 v60, v52
	v_pk_mul_f32 v[40:41], v[40:41], v[56:57]
	v_pk_add_f32 v[44:45], v[58:59], 1.0 op_sel_hi:[1,0]
	v_pk_fma_f32 v[42:43], v[42:43], v[46:47], v[54:55]
	v_pk_fma_f32 v[40:41], v[40:41], v[44:45], v[60:61]
	v_and_b32_sdwa v46, v43, v94 dst_sel:DWORD dst_unused:UNUSED_PAD src0_sel:WORD_1 src1_sel:DWORD
	v_and_b32_sdwa v47, v42, v94 dst_sel:DWORD dst_unused:UNUSED_PAD src0_sel:WORD_1 src1_sel:DWORD
	v_and_b32_sdwa v44, v41, v94 dst_sel:DWORD dst_unused:UNUSED_PAD src0_sel:WORD_1 src1_sel:DWORD
	v_and_b32_sdwa v45, v40, v94 dst_sel:DWORD dst_unused:UNUSED_PAD src0_sel:WORD_1 src1_sel:DWORD
	v_add3_u32 v43, v43, v46, s15
	v_add3_u32 v42, v42, v47, s15
	v_add3_u32 v40, v40, v45, s15
	v_add3_u32 v41, v41, v44, s15
	v_and_b32_e32 v43, 0xffff0000, v43
	v_and_b32_e32 v42, 0xffff0000, v42
	v_or_b32_sdwa v41, v43, v41 dst_sel:DWORD dst_unused:UNUSED_PAD src0_sel:DWORD src1_sel:WORD_1
	v_or_b32_sdwa v40, v42, v40 dst_sel:DWORD dst_unused:UNUSED_PAD src0_sel:DWORD src1_sel:WORD_1
	global_store_dwordx2 v[78:79], v[40:41], off offset:512
	s_nop 1
	v_mov_b64_e32 v[40:41], v[180:181]
	v_mov_b64_e32 v[42:43], v[182:183]
	s_nop 0
	s_nop 1
	v_mov_b64_e32 v[44:45], v[188:189]
	v_mov_b64_e32 v[46:47], v[190:191]
	s_nop 1
	v_mov_b64_e32 v[48:49], v[192:193]
	v_mov_b64_e32 v[50:51], v[194:195]
	v_mov_b32_e32 v52, v4
	v_mov_b32_e32 v53, v6
	v_mov_b32_e32 v6, v5
	v_pk_mul_f32 v[4:5], v[52:53], v[80:81] op_sel_hi:[1,0]
	v_pk_mul_f32 v[6:7], v[6:7], v[80:81] op_sel_hi:[1,0]
	s_waitcnt vmcnt(6)
; __device__ __forceinline__ unsigned pk2(float lo, float hi) { return f2bf(lo) | (f2bf(hi) << 16); }
; template <int PH>
; __device__ __forceinline__ void run_phase(const Args& args, LAS unsigned char* lds) {
;     ...
;                 u32x2* op = (u32x2*)(Hb + (size_t)row * D);
; #pragma unroll
;                 for (int j = 0; j < 8; ++j) { const int c4 = lane + 64 * j; const f32x4 gg = ((const f32x4*)g)[c4], sh = ((const f32x4*)mr)[c4], sc = ((const f32x4*)(mr + D))[c4];
;                     u32x2 w; w.x = pk2(v[j].x * rs * gg.x * (1.f + sc.x) + sh.x, v[j].y * rs * gg.y * (1.f + sc.y) + sh.y);
;                     w.y = pk2(v[j].z * rs * gg.z * (1.f + sc.z) + sh.z, v[j].w * rs * gg.w * (1.f + sc.w) + sh.w); op[c4] = w; }
; #pragma unroll
;                 for (int j = 0; j < 8; ++j) v[j] = nv[j];
	v_mov_b64_e32 v[62:63], v[38:39]
	v_mov_b64_e32 v[60:61], v[36:37]
	v_mov_b32_e32 v53, v42
	v_mov_b32_e32 v55, v46
	v_mov_b32_e32 v42, v41
	v_mov_b32_e32 v46, v45
	v_mov_b32_e32 v52, v40
	v_mov_b32_e32 v54, v44
	v_mov_b32_e32 v57, v50
	v_mov_b32_e32 v50, v49
	v_pk_mul_f32 v[6:7], v[6:7], v[42:43]
	v_pk_add_f32 v[42:43], v[46:47], 1.0 op_sel_hi:[1,0]
	v_mov_b32_e32 v56, v48
	v_pk_mul_f32 v[4:5], v[4:5], v[52:53]
	v_pk_add_f32 v[40:41], v[54:55], 1.0 op_sel_hi:[1,0]
	v_pk_fma_f32 v[6:7], v[6:7], v[42:43], v[50:51]
	v_pk_fma_f32 v[4:5], v[4:5], v[40:41], v[56:57]
	v_and_b32_sdwa v42, v7, v94 dst_sel:DWORD dst_unused:UNUSED_PAD src0_sel:WORD_1 src1_sel:DWORD
	v_and_b32_sdwa v43, v6, v94 dst_sel:DWORD dst_unused:UNUSED_PAD src0_sel:WORD_1 src1_sel:DWORD
	v_and_b32_sdwa v40, v5, v94 dst_sel:DWORD dst_unused:UNUSED_PAD src0_sel:WORD_1 src1_sel:DWORD
	v_and_b32_sdwa v41, v4, v94 dst_sel:DWORD dst_unused:UNUSED_PAD src0_sel:WORD_1 src1_sel:DWORD
	v_add3_u32 v7, v7, v42, s15
	v_add3_u32 v6, v6, v43, s15
	v_add3_u32 v4, v4, v41, s15
	v_add3_u32 v5, v5, v40, s15
	v_and_b32_e32 v7, 0xffff0000, v7
	v_and_b32_e32 v6, 0xffff0000, v6
	v_or_b32_sdwa v5, v7, v5 dst_sel:DWORD dst_unused:UNUSED_PAD src0_sel:DWORD src1_sel:WORD_1
	v_or_b32_sdwa v4, v6, v4 dst_sel:DWORD dst_unused:UNUSED_PAD src0_sel:DWORD src1_sel:WORD_1
	global_store_dwordx2 v[78:79], v[4:5], off offset:1024
	s_nop 1
	v_mov_b64_e32 v[96:97], v[196:197]
	v_mov_b64_e32 v[98:99], v[198:199]
	s_nop 1
	v_mov_b64_e32 v[100:101], v[200:201]
	v_mov_b64_e32 v[102:103], v[202:203]
	s_nop 1
	v_mov_b64_e32 v[104:105], v[204:205]
	v_mov_b64_e32 v[106:107], v[206:207]
	v_mov_b32_e32 v4, v0
	v_mov_b32_e32 v5, v2
	v_mov_b32_e32 v2, v1
	v_pk_mul_f32 v[108:109], v[4:5], v[80:81] op_sel_hi:[1,0]
	v_pk_mul_f32 v[110:111], v[2:3], v[80:81] op_sel_hi:[1,0]
	v_mov_b64_e32 v[58:59], v[34:35]
	v_mov_b64_e32 v[54:55], v[30:31]
	v_mov_b64_e32 v[50:51], v[26:27]
	v_mov_b64_e32 v[46:47], v[22:23]
	v_mov_b64_e32 v[42:43], v[18:19]
	v_mov_b64_e32 v[4:5], v[12:13]
	v_mov_b64_e32 v[0:1], v[8:9]
	v_mov_b64_e32 v[56:57], v[32:33]
	v_mov_b64_e32 v[52:53], v[28:29]
	v_mov_b64_e32 v[48:49], v[24:25]
	v_mov_b64_e32 v[44:45], v[20:21]
	v_mov_b64_e32 v[40:41], v[16:17]
	v_mov_b64_e32 v[6:7], v[14:15]
	v_mov_b64_e32 v[2:3], v[10:11]
	v_mov_b32_e32 v112, v96
	v_mov_b32_e32 v113, v98
	v_mov_b32_e32 v114, v100
	v_mov_b32_e32 v115, v102
	v_mov_b32_e32 v98, v97
	v_mov_b32_e32 v102, v101
	v_mov_b32_e32 v116, v104
	v_mov_b32_e32 v117, v106
	v_mov_b32_e32 v106, v105
	v_pk_mul_f32 v[96:97], v[108:109], v[112:113]
	v_pk_add_f32 v[100:101], v[114:115], 1.0 op_sel_hi:[1,0]
	v_pk_mul_f32 v[98:99], v[110:111], v[98:99]
	v_pk_add_f32 v[102:103], v[102:103], 1.0 op_sel_hi:[1,0]
	v_pk_fma_f32 v[96:97], v[96:97], v[100:101], v[116:117]
	v_pk_fma_f32 v[98:99], v[98:99], v[102:103], v[106:107]
	v_and_b32_sdwa v80, v97, v94 dst_sel:DWORD dst_unused:UNUSED_PAD src0_sel:WORD_1 src1_sel:DWORD
	v_and_b32_sdwa v95, v96, v94 dst_sel:DWORD dst_unused:UNUSED_PAD src0_sel:WORD_1 src1_sel:DWORD
	v_and_b32_sdwa v100, v99, v94 dst_sel:DWORD dst_unused:UNUSED_PAD src0_sel:WORD_1 src1_sel:DWORD
	v_and_b32_sdwa v101, v98, v94 dst_sel:DWORD dst_unused:UNUSED_PAD src0_sel:WORD_1 src1_sel:DWORD
	v_add3_u32 v95, v96, v95, s15
	v_add3_u32 v80, v97, v80, s15
	v_add3_u32 v96, v99, v100, s15
	v_add3_u32 v97, v98, v101, s15
	v_and_b32_e32 v96, 0xffff0000, v96
	v_and_b32_e32 v98, 0xffff0000, v97
	v_or_b32_sdwa v97, v96, v80 dst_sel:DWORD dst_unused:UNUSED_PAD src0_sel:DWORD src1_sel:WORD_1
	v_or_b32_sdwa v96, v98, v95 dst_sel:DWORD dst_unused:UNUSED_PAD src0_sel:DWORD src1_sel:WORD_1
	global_store_dwordx2 v[78:79], v[96:97], off offset:1536
	v_lshl_add_u64 v[78:79], v[78:79], 0, s[4:5]
	s_cbranch_scc1 .LBB0_154
.LBB0_152:
	v_lshlrev_b32_e32 v95, 4, v66
	s_branch .LBB0_151
